# c21a + MLA row-sum chain spread over the first 16 QK MFMA gaps (2 adds per gap) instead of the last 8
# speedup vs baseline: 1.0039x; 1.0039x over previous
.LBB0_871:
	s_add_i32 s80, s75, -3
	s_lshl_b32 s76, s74, 14
	s_add_i32 s8, s69, s76
	v_lshl_add_u64 v[2:3], v[226:227], 0, s[34:35]
	s_mov_b32 m0, s8
	s_nop 0
	global_load_lds_dwordx4 v[2:3], off
	s_add_i32 m0, s8, 0x2000
	s_mul_i32 s8, s60, 0x6300
	s_add_i32 s61, s68, s8
	global_load_lds_dwordx4 v[226:227], off
	s_add_i32 m0, s61, 0xc000
	s_add_i32 s8, s75, -1
	s_cmp_lt_u32 s8, s77
	s_cselect_b32 s8, s8, s73
	s_lshl_b32 s8, s8, 6
	s_lshl_b64 s[58:59], s[8:9], 12
	v_lshl_add_u64 v[2:3], v[218:219], 0, s[58:59]
	global_load_lds_dwordx4 v[2:3], off
	v_lshl_add_u64 v[2:3], v[2:3], 0, s[12:13]
	s_add_i32 m0, s61, 0xe100
	s_lshl_b64 s[82:83], s[8:9], 7
	global_load_lds_dwordx4 v[2:3], off
	v_lshl_add_u64 v[2:3], v[224:225], 0, s[82:83]
	s_add_i32 m0, s61, 0x10200
	s_nop 0
	global_load_lds_dwordx4 v[2:3], off
	s_mul_i32 s8, s79, 0x6300
	s_add_i32 s8, s8, 0
	v_add_u32_e32 v0, s8, v237
	ds_read_b128 v[2:5], v0 offset:49152
	ds_read_b128 v[6:9], v0 offset:50176
	v_add_f32_e32 v247, v96, v97
	v_add_f32_e32 v247, v98, v247
	s_waitcnt lgkmcnt(0)
	v_mfma_f32_32x32x16_bf16 v[112:127], v[2:5], v[188:191], 0
	v_add_f32_e32 v247, v99, v247
	v_add_f32_e32 v247, v100, v247
	v_mfma_f32_32x32x16_bf16 v[128:143], v[6:9], v[188:191], 0
	ds_read_b128 v[2:5], v0 offset:51264
	ds_read_b128 v[6:9], v0 offset:52288
	v_add_f32_e32 v247, v101, v247
	v_add_f32_e32 v247, v102, v247
	s_waitcnt lgkmcnt(0)
	v_mfma_f32_32x32x16_bf16 v[112:127], v[2:5], v[184:187], v[112:127]
	v_add_f32_e32 v247, v103, v247
	v_add_f32_e32 v247, v104, v247
	v_mfma_f32_32x32x16_bf16 v[128:143], v[6:9], v[184:187], v[128:143]
	ds_read_b128 v[2:5], v0 offset:53376
	ds_read_b128 v[6:9], v0 offset:54400
	v_add_f32_e32 v247, v105, v247
	v_add_f32_e32 v247, v106, v247
	s_waitcnt lgkmcnt(0)
	v_mfma_f32_32x32x16_bf16 v[112:127], v[2:5], v[180:183], v[112:127]
	v_add_f32_e32 v247, v107, v247
	v_add_f32_e32 v247, v108, v247
	v_mfma_f32_32x32x16_bf16 v[128:143], v[6:9], v[180:183], v[128:143]
	ds_read_b128 v[2:5], v0 offset:55488
	ds_read_b128 v[6:9], v0 offset:56512
	v_add_f32_e32 v247, v109, v247
	v_add_f32_e32 v247, v110, v247
	s_waitcnt lgkmcnt(0)
	v_mfma_f32_32x32x16_bf16 v[112:127], v[2:5], v[176:179], v[112:127]
	v_add_f32_e32 v247, v111, v247
	v_add_f32_e32 v247, v80, v247
	v_mfma_f32_32x32x16_bf16 v[128:143], v[6:9], v[176:179], v[128:143]
	ds_read_b128 v[2:5], v0 offset:57600
	ds_read_b128 v[6:9], v0 offset:58624
	v_add_f32_e32 v247, v81, v247
	v_add_f32_e32 v247, v82, v247
	s_waitcnt lgkmcnt(0)
	v_mfma_f32_32x32x16_bf16 v[112:127], v[2:5], v[172:175], v[112:127]
	v_add_f32_e32 v247, v83, v247
	v_add_f32_e32 v247, v84, v247
	v_mfma_f32_32x32x16_bf16 v[128:143], v[6:9], v[172:175], v[128:143]
	ds_read_b128 v[2:5], v0 offset:59712
	ds_read_b128 v[6:9], v0 offset:60736
	v_add_f32_e32 v247, v85, v247
	v_add_f32_e32 v247, v86, v247
	s_waitcnt lgkmcnt(0)
	v_mfma_f32_32x32x16_bf16 v[112:127], v[2:5], v[168:171], v[112:127]
	v_add_f32_e32 v247, v87, v247
	v_add_f32_e32 v247, v88, v247
	v_mfma_f32_32x32x16_bf16 v[128:143], v[6:9], v[168:171], v[128:143]
	ds_read_b128 v[2:5], v0 offset:61824
	ds_read_b128 v[6:9], v0 offset:62848
	v_add_f32_e32 v247, v89, v247
	v_add_f32_e32 v247, v90, v247
	s_waitcnt lgkmcnt(0)
	v_mfma_f32_32x32x16_bf16 v[112:127], v[2:5], v[164:167], v[112:127]
	v_add_f32_e32 v247, v91, v247
	v_add_f32_e32 v247, v92, v247
	v_mfma_f32_32x32x16_bf16 v[128:143], v[6:9], v[164:167], v[128:143]
	ds_read_b128 v[2:5], v0 offset:63936
	ds_read_b128 v[6:9], v0 offset:64960
	v_add_f32_e32 v247, v93, v247
	v_add_f32_e32 v247, v94, v247
	v_add_u32_e32 v0, 0xc000, v0
	s_waitcnt lgkmcnt(0)
	v_mfma_f32_32x32x16_bf16 v[112:127], v[2:5], v[160:163], v[112:127]
	ds_read_b128 v[2:5], v0 offset:17920
	ds_read_b128 v[10:13], v0 offset:16896
	v_mfma_f32_32x32x16_bf16 v[128:143], v[6:9], v[160:163], v[128:143]
	ds_read_b128 v[6:9], v0 offset:20032
	ds_read_b128 v[192:195], v0 offset:19008
	ds_read_b128 v[196:199], v0 offset:22144
	ds_read_b128 v[200:203], v0 offset:21120
	ds_read_b128 v[204:207], v0 offset:24256
	ds_read_b128 v[208:211], v0 offset:23232
	s_waitcnt lgkmcnt(0)
	v_mfma_f32_32x32x16_bf16 v[112:127], v[10:13], v[156:159], v[112:127]
	v_mfma_f32_32x32x16_bf16 v[128:143], v[2:5], v[156:159], v[128:143]
	v_mfma_f32_32x32x16_bf16 v[112:127], v[192:195], v[152:155], v[112:127]
	v_mfma_f32_32x32x16_bf16 v[128:143], v[6:9], v[152:155], v[128:143]
	v_add_f32_e32 v14, v95, v247
	v_mov_b32_e32 v15, v14
	s_nop 1
	v_permlane32_swap_b32_e32 v14, v15
	v_mfma_f32_32x32x16_bf16 v[112:127], v[200:203], v[148:151], v[112:127]
	v_cvt_pk_bf16_f32 v192, v96, v97
	v_cvt_pk_bf16_f32 v193, v98, v99
	v_cvt_pk_bf16_f32 v194, v100, v101
	v_cvt_pk_bf16_f32 v195, v102, v103
	v_cvt_pk_bf16_f32 v10, v104, v105
	v_cvt_pk_bf16_f32 v11, v106, v107
	v_cvt_pk_bf16_f32 v12, v108, v109
	v_mfma_f32_32x32x16_bf16 v[128:143], v[196:199], v[148:151], v[128:143]
	v_cvt_pk_bf16_f32 v13, v110, v111
	v_cvt_pk_bf16_f32 v6, v80, v81
	v_cvt_pk_bf16_f32 v7, v82, v83
	v_cvt_pk_bf16_f32 v8, v84, v85
	v_cvt_pk_bf16_f32 v9, v86, v87
	v_cvt_pk_bf16_f32 v2, v88, v89
	v_cvt_pk_bf16_f32 v3, v90, v91
	v_mfma_f32_32x32x16_bf16 v[112:127], v[208:211], v[144:147], v[112:127]
	v_cvt_pk_bf16_f32 v4, v92, v93
	v_cvt_pk_bf16_f32 v5, v94, v95
	v_mfma_f32_32x32x16_bf16 v[128:143], v[204:207], v[144:147], v[128:143]
	s_cmp_gt_i32 s80, s72
	s_cbranch_scc1 .Lold_mla_odd
	v_lshl_add_u32 v0, s60, 14, v235
	ds_read_b64_tr_b16 v[208:209], v0 offset:0
	ds_read_b64_tr_b16 v[210:211], v0 offset:0x800
	ds_read_b64_tr_b16 v[204:205], v0 offset:0x1000
	ds_read_b64_tr_b16 v[206:207], v0 offset:0x1800
	ds_read_b64_tr_b16 v[200:201], v0 offset:0x2000
	ds_read_b64_tr_b16 v[202:203], v0 offset:0x2800
	ds_read_b64_tr_b16 v[196:197], v0 offset:0x3000
	ds_read_b64_tr_b16 v[198:199], v0 offset:0x3800
	s_nop 1
	v_max3_f32 v245, v112, v113, v114
	v_max3_f32 v246, v128, v129, v130
	v_max3_f32 v245, v245, v115, v116
	v_max3_f32 v246, v246, v131, v132
	v_max3_f32 v245, v245, v117, v118
	v_max3_f32 v246, v246, v133, v134
	v_max3_f32 v245, v245, v119, v120
	v_max3_f32 v246, v246, v135, v136
	v_max3_f32 v245, v245, v121, v122
	v_max3_f32 v246, v246, v137, v138
	v_max3_f32 v245, v245, v123, v124
	v_max3_f32 v246, v246, v139, v140
	v_max3_f32 v245, v245, v125, v126
	v_max3_f32 v246, v246, v141, v142
	v_max_f32_e32 v245, v245, v127
	v_max_f32_e32 v246, v246, v143
	v_max_f32_e32 v245, v245, v246
	v_mov_b32_e32 v246, v245
	s_nop 1
	v_permlane32_swap_b32_e32 v245, v246
	v_max_f32_e32 v245, v245, v246
	v_sub_f32_e32 v246, v245, v236
	v_cmp_ge_f32_e32 vcc, s29, v246
	s_cmp_eq_u64 vcc, exec
	v_mov_b32_e32 v240, 1.0
	s_cbranch_scc0 .Lfm_odd_ev

.LBB0_876:
	s_waitcnt vmcnt(0)
	s_add_i32 s60, s74, 1
	s_cmp_lg_u32 s74, 2
	s_cselect_b32 s81, s60, 0
	s_waitcnt vmcnt(0)
	s_barrier
	s_lshl_b32 s78, s81, 14
	s_add_i32 s60, s69, s78
	v_lshl_add_u64 v[2:3], v[222:223], 0, s[58:59]
	v_lshl_add_u64 v[4:5], v[2:3], 0, s[14:15]
	s_mov_b32 m0, s60
	s_add_i32 s8, s8, s70
	global_load_lds_dwordx4 v[4:5], off
	v_lshl_add_u64 v[2:3], v[2:3], 0, s[16:17]
	s_add_i32 m0, s60, 0x2000
	s_add_i32 s82, s8, s71
	global_load_lds_dwordx4 v[2:3], off
	s_add_i32 m0, s82, 0xc000
	s_cmp_ge_u32 s75, s77
	s_cselect_b64 s[58:59], -1, 0
	s_cmp_lt_u32 s75, s77
	s_cselect_b32 s8, s75, s73
	s_lshl_b32 s8, s8, 6
	s_lshl_b64 s[60:61], s[8:9], 12
	v_lshl_add_u64 v[2:3], v[218:219], 0, s[60:61]
	global_load_lds_dwordx4 v[2:3], off
	v_lshl_add_u64 v[2:3], v[2:3], 0, s[12:13]
	s_add_i32 m0, s82, 0xe100
	s_lshl_b64 s[60:61], s[8:9], 7
	global_load_lds_dwordx4 v[2:3], off
	v_lshl_add_u64 v[2:3], v[224:225], 0, s[60:61]
	s_add_i32 m0, s82, 0x10200
	s_nop 0
	global_load_lds_dwordx4 v[2:3], off
	s_mul_i32 s8, s74, 0x6300
	v_add_u32_e32 v0, s8, v238
	ds_read_b128 v[2:5], v0 offset:49152
	ds_read_b128 v[6:9], v0 offset:50176
	v_add_f32_e32 v247, v96, v97
	v_add_f32_e32 v247, v98, v247
	s_waitcnt lgkmcnt(0)
	v_mfma_f32_32x32x16_bf16 v[112:127], v[2:5], v[188:191], 0
	v_add_f32_e32 v247, v99, v247
	v_add_f32_e32 v247, v100, v247
	v_mfma_f32_32x32x16_bf16 v[128:143], v[6:9], v[188:191], 0
	ds_read_b128 v[2:5], v0 offset:51264
	ds_read_b128 v[6:9], v0 offset:52288
	v_add_f32_e32 v247, v101, v247
	v_add_f32_e32 v247, v102, v247
	s_waitcnt lgkmcnt(0)
	v_mfma_f32_32x32x16_bf16 v[112:127], v[2:5], v[184:187], v[112:127]
	v_add_f32_e32 v247, v103, v247
	v_add_f32_e32 v247, v104, v247
	v_mfma_f32_32x32x16_bf16 v[128:143], v[6:9], v[184:187], v[128:143]
	ds_read_b128 v[2:5], v0 offset:53376
	ds_read_b128 v[6:9], v0 offset:54400
	v_add_f32_e32 v247, v105, v247
	v_add_f32_e32 v247, v106, v247
	s_waitcnt lgkmcnt(0)
	v_mfma_f32_32x32x16_bf16 v[112:127], v[2:5], v[180:183], v[112:127]
	v_add_f32_e32 v247, v107, v247
	v_add_f32_e32 v247, v108, v247
	v_mfma_f32_32x32x16_bf16 v[128:143], v[6:9], v[180:183], v[128:143]
	ds_read_b128 v[2:5], v0 offset:55488
	ds_read_b128 v[6:9], v0 offset:56512
	v_add_f32_e32 v247, v109, v247
	v_add_f32_e32 v247, v110, v247
	s_waitcnt lgkmcnt(0)
	v_mfma_f32_32x32x16_bf16 v[112:127], v[2:5], v[176:179], v[112:127]
	v_add_f32_e32 v247, v111, v247
	v_add_f32_e32 v247, v80, v247
	v_mfma_f32_32x32x16_bf16 v[128:143], v[6:9], v[176:179], v[128:143]
	ds_read_b128 v[2:5], v0 offset:57600
	ds_read_b128 v[6:9], v0 offset:58624
	v_add_f32_e32 v247, v81, v247
	v_add_f32_e32 v247, v82, v247
	s_waitcnt lgkmcnt(0)
	v_mfma_f32_32x32x16_bf16 v[112:127], v[2:5], v[172:175], v[112:127]
	v_add_f32_e32 v247, v83, v247
	v_add_f32_e32 v247, v84, v247
	v_mfma_f32_32x32x16_bf16 v[128:143], v[6:9], v[172:175], v[128:143]
	ds_read_b128 v[2:5], v0 offset:59712
	ds_read_b128 v[6:9], v0 offset:60736
	v_add_f32_e32 v247, v85, v247
	v_add_f32_e32 v247, v86, v247
	s_waitcnt lgkmcnt(0)
	v_mfma_f32_32x32x16_bf16 v[112:127], v[2:5], v[168:171], v[112:127]
	v_add_f32_e32 v247, v87, v247
	v_add_f32_e32 v247, v88, v247
	v_mfma_f32_32x32x16_bf16 v[128:143], v[6:9], v[168:171], v[128:143]
	ds_read_b128 v[2:5], v0 offset:61824
	ds_read_b128 v[6:9], v0 offset:62848
	v_add_f32_e32 v247, v89, v247
	v_add_f32_e32 v247, v90, v247
	s_waitcnt lgkmcnt(0)
	v_mfma_f32_32x32x16_bf16 v[112:127], v[2:5], v[164:167], v[112:127]
	v_add_f32_e32 v247, v91, v247
	v_add_f32_e32 v247, v92, v247
	v_mfma_f32_32x32x16_bf16 v[128:143], v[6:9], v[164:167], v[128:143]
	ds_read_b128 v[2:5], v0 offset:63936
	ds_read_b128 v[6:9], v0 offset:64960
	v_add_f32_e32 v247, v93, v247
	v_add_f32_e32 v247, v94, v247
	v_add_u32_e32 v0, 0xc000, v0
	s_waitcnt lgkmcnt(0)
	v_mfma_f32_32x32x16_bf16 v[112:127], v[2:5], v[160:163], v[112:127]
	ds_read_b128 v[2:5], v0 offset:17920
	ds_read_b128 v[10:13], v0 offset:16896
	v_mfma_f32_32x32x16_bf16 v[128:143], v[6:9], v[160:163], v[128:143]
	ds_read_b128 v[6:9], v0 offset:20032
	ds_read_b128 v[192:195], v0 offset:19008
	ds_read_b128 v[196:199], v0 offset:22144
	ds_read_b128 v[200:203], v0 offset:21120
	ds_read_b128 v[204:207], v0 offset:24256
	ds_read_b128 v[208:211], v0 offset:23232
	s_waitcnt lgkmcnt(0)
	v_mfma_f32_32x32x16_bf16 v[112:127], v[10:13], v[156:159], v[112:127]
	v_mfma_f32_32x32x16_bf16 v[128:143], v[2:5], v[156:159], v[128:143]
	v_mfma_f32_32x32x16_bf16 v[112:127], v[192:195], v[152:155], v[112:127]
	v_mfma_f32_32x32x16_bf16 v[128:143], v[6:9], v[152:155], v[128:143]
	v_add_f32_e32 v241, v95, v247
	v_mov_b32_e32 v242, v241
	s_nop 1
	v_permlane32_swap_b32_e32 v241, v242
	v_mfma_f32_32x32x16_bf16 v[112:127], v[200:203], v[148:151], v[112:127]
	v_cvt_pk_bf16_f32 v192, v96, v97
	v_cvt_pk_bf16_f32 v193, v98, v99
	v_cvt_pk_bf16_f32 v194, v100, v101
	v_cvt_pk_bf16_f32 v195, v102, v103
	v_cvt_pk_bf16_f32 v10, v104, v105
	v_cvt_pk_bf16_f32 v11, v106, v107
	v_cvt_pk_bf16_f32 v12, v108, v109
	v_mfma_f32_32x32x16_bf16 v[128:143], v[196:199], v[148:151], v[128:143]
	v_cvt_pk_bf16_f32 v13, v110, v111
	v_cvt_pk_bf16_f32 v6, v80, v81
	v_cvt_pk_bf16_f32 v7, v82, v83
	v_cvt_pk_bf16_f32 v8, v84, v85
	v_cvt_pk_bf16_f32 v9, v86, v87
	v_cvt_pk_bf16_f32 v2, v88, v89
	v_cvt_pk_bf16_f32 v3, v90, v91
	v_mfma_f32_32x32x16_bf16 v[112:127], v[208:211], v[144:147], v[112:127]
	v_cvt_pk_bf16_f32 v4, v92, v93
	v_cvt_pk_bf16_f32 v5, v94, v95
	v_mfma_f32_32x32x16_bf16 v[128:143], v[204:207], v[144:147], v[128:143]
	s_cmp_lt_i32 s80, s72
	s_cbranch_scc0 .Lold_mla_even
	v_lshl_add_u32 v243, s79, 14, v235
	ds_read_b64_tr_b16 v[208:209], v243 offset:0
	ds_read_b64_tr_b16 v[210:211], v243 offset:0x800
	ds_read_b64_tr_b16 v[204:205], v243 offset:0x1000
	ds_read_b64_tr_b16 v[206:207], v243 offset:0x1800
	ds_read_b64_tr_b16 v[200:201], v243 offset:0x2000
	ds_read_b64_tr_b16 v[202:203], v243 offset:0x2800
	ds_read_b64_tr_b16 v[196:197], v243 offset:0x3000
	ds_read_b64_tr_b16 v[198:199], v243 offset:0x3800
	s_nop 1
	v_max3_f32 v245, v112, v113, v114
	v_max3_f32 v246, v128, v129, v130
	v_max3_f32 v245, v245, v115, v116
	v_max3_f32 v246, v246, v131, v132
	v_max3_f32 v245, v245, v117, v118
	v_max3_f32 v246, v246, v133, v134
	v_max3_f32 v245, v245, v119, v120
	v_max3_f32 v246, v246, v135, v136
	v_max3_f32 v245, v245, v121, v122
	v_max3_f32 v246, v246, v137, v138
	v_max3_f32 v245, v245, v123, v124
	v_max3_f32 v246, v246, v139, v140
	v_max3_f32 v245, v245, v125, v126
	v_max3_f32 v246, v246, v141, v142
	v_max_f32_e32 v245, v245, v127
	v_max_f32_e32 v246, v246, v143
	v_max_f32_e32 v245, v245, v246
	v_mov_b32_e32 v246, v245
	s_nop 1
	v_permlane32_swap_b32_e32 v245, v246
	v_max_f32_e32 v245, v245, v246
	v_sub_f32_e32 v246, v245, v236
	v_cmp_ge_f32_e32 vcc, s29, v246
	s_cmp_eq_u64 vcc, exec
	v_mov_b32_e32 v0, 1.0
	s_cbranch_scc0 .Lfm_even_ev
